# plus prologue weight transposes: the 16 per-tile RMSNorm-gain loads are issued together behind one wait instead of 16 serialized load/wait pairs
# baseline (speedup 1.0000x reference)
.LBB0_44:
	s_or_b64 exec, exec, s[12:13]
	s_waitcnt lgkmcnt(0)
	s_cmp_lg_u64 s[10:11], 0
	s_cbranch_scc0 .LBB0_46
	v_ashrrev_i32_e32 v163, 31, v162
	v_lshl_add_u64 v[4:5], v[162:163], 2, s[10:11]
	global_load_dword v170, v[4:5], off
	global_load_dword v172, v[4:5], off offset:16
	global_load_dword v174, v[4:5], off offset:32
	global_load_dword v176, v[4:5], off offset:48
	global_load_dword v178, v[4:5], off offset:64
	global_load_dword v180, v[4:5], off offset:80
	global_load_dword v182, v[4:5], off offset:96
	global_load_dword v184, v[4:5], off offset:112
	global_load_dword v186, v[4:5], off offset:128
	global_load_dword v188, v[4:5], off offset:144
	global_load_dword v190, v[4:5], off offset:160
	global_load_dword v192, v[4:5], off offset:176
	global_load_dword v194, v[4:5], off offset:192
	global_load_dword v196, v[4:5], off offset:208
	global_load_dword v198, v[4:5], off offset:224
	global_load_dword v200, v[4:5], off offset:240
	s_waitcnt vmcnt(0)
	v_pk_mul_f32 v[72:73], v[72:73], v[170:171] op_sel_hi:[1,0]
	v_pk_mul_f32 v[70:71], v[70:71], v[170:171] op_sel_hi:[1,0]
	v_pk_mul_f32 v[76:77], v[76:77], v[172:173] op_sel_hi:[1,0]
	v_pk_mul_f32 v[74:75], v[74:75], v[172:173] op_sel_hi:[1,0]
	v_pk_mul_f32 v[80:81], v[80:81], v[174:175] op_sel_hi:[1,0]
	v_pk_mul_f32 v[78:79], v[78:79], v[174:175] op_sel_hi:[1,0]
	v_pk_mul_f32 v[84:85], v[84:85], v[176:177] op_sel_hi:[1,0]
	v_pk_mul_f32 v[82:83], v[82:83], v[176:177] op_sel_hi:[1,0]
	v_pk_mul_f32 v[88:89], v[88:89], v[178:179] op_sel_hi:[1,0]
	v_pk_mul_f32 v[86:87], v[86:87], v[178:179] op_sel_hi:[1,0]
	v_pk_mul_f32 v[92:93], v[92:93], v[180:181] op_sel_hi:[1,0]
	v_pk_mul_f32 v[90:91], v[90:91], v[180:181] op_sel_hi:[1,0]
	v_pk_mul_f32 v[96:97], v[96:97], v[182:183] op_sel_hi:[1,0]
	v_pk_mul_f32 v[94:95], v[94:95], v[182:183] op_sel_hi:[1,0]
	v_pk_mul_f32 v[100:101], v[100:101], v[184:185] op_sel_hi:[1,0]
	v_pk_mul_f32 v[98:99], v[98:99], v[184:185] op_sel_hi:[1,0]
	v_pk_mul_f32 v[104:105], v[104:105], v[186:187] op_sel_hi:[1,0]
	v_pk_mul_f32 v[102:103], v[102:103], v[186:187] op_sel_hi:[1,0]
	v_pk_mul_f32 v[108:109], v[108:109], v[188:189] op_sel_hi:[1,0]
	v_pk_mul_f32 v[106:107], v[106:107], v[188:189] op_sel_hi:[1,0]
	v_pk_mul_f32 v[112:113], v[112:113], v[190:191] op_sel_hi:[1,0]
	v_pk_mul_f32 v[110:111], v[110:111], v[190:191] op_sel_hi:[1,0]
	v_pk_mul_f32 v[116:117], v[116:117], v[192:193] op_sel_hi:[1,0]
	v_pk_mul_f32 v[114:115], v[114:115], v[192:193] op_sel_hi:[1,0]
	v_pk_mul_f32 v[120:121], v[120:121], v[194:195] op_sel_hi:[1,0]
	v_pk_mul_f32 v[118:119], v[118:119], v[194:195] op_sel_hi:[1,0]
	v_pk_mul_f32 v[124:125], v[124:125], v[196:197] op_sel_hi:[1,0]
	v_pk_mul_f32 v[122:123], v[122:123], v[196:197] op_sel_hi:[1,0]
	v_pk_mul_f32 v[128:129], v[128:129], v[198:199] op_sel_hi:[1,0]
	v_pk_mul_f32 v[126:127], v[126:127], v[198:199] op_sel_hi:[1,0]
	v_pk_mul_f32 v[132:133], v[132:133], v[200:201] op_sel_hi:[1,0]
	v_pk_mul_f32 v[130:131], v[130:131], v[200:201] op_sel_hi:[1,0]

.LBB0_79:
	s_or_b64 exec, exec, s[16:17]
	s_waitcnt lgkmcnt(0)
	s_cmp_lg_u64 s[12:13], 0
	s_cbranch_scc0 .LBB0_81
	v_ashrrev_i32_e32 v5, 31, v4
	v_lshl_add_u64 v[4:5], v[4:5], 2, s[12:13]
	global_load_dword v170, v[4:5], off
	global_load_dword v172, v[4:5], off offset:16
	global_load_dword v174, v[4:5], off offset:32
	global_load_dword v176, v[4:5], off offset:48
	global_load_dword v178, v[4:5], off offset:64
	global_load_dword v180, v[4:5], off offset:80
	global_load_dword v182, v[4:5], off offset:96
	global_load_dword v184, v[4:5], off offset:112
	global_load_dword v186, v[4:5], off offset:128
	global_load_dword v188, v[4:5], off offset:144
	global_load_dword v190, v[4:5], off offset:160
	global_load_dword v192, v[4:5], off offset:176
	global_load_dword v194, v[4:5], off offset:192
	global_load_dword v196, v[4:5], off offset:208
	global_load_dword v198, v[4:5], off offset:224
	global_load_dword v200, v[4:5], off offset:240
	s_waitcnt vmcnt(0)
	v_pk_mul_f32 v[8:9], v[8:9], v[170:171] op_sel_hi:[1,0]
	v_pk_mul_f32 v[6:7], v[6:7], v[170:171] op_sel_hi:[1,0]
	v_pk_mul_f32 v[12:13], v[12:13], v[172:173] op_sel_hi:[1,0]
	v_pk_mul_f32 v[10:11], v[10:11], v[172:173] op_sel_hi:[1,0]
	v_pk_mul_f32 v[20:21], v[20:21], v[174:175] op_sel_hi:[1,0]
	v_pk_mul_f32 v[18:19], v[18:19], v[174:175] op_sel_hi:[1,0]
	v_pk_mul_f32 v[16:17], v[16:17], v[176:177] op_sel_hi:[1,0]
	v_pk_mul_f32 v[14:15], v[14:15], v[176:177] op_sel_hi:[1,0]
	v_pk_mul_f32 v[28:29], v[28:29], v[178:179] op_sel_hi:[1,0]
	v_pk_mul_f32 v[26:27], v[26:27], v[178:179] op_sel_hi:[1,0]
	v_pk_mul_f32 v[24:25], v[24:25], v[180:181] op_sel_hi:[1,0]
	v_pk_mul_f32 v[22:23], v[22:23], v[180:181] op_sel_hi:[1,0]
	v_pk_mul_f32 v[36:37], v[36:37], v[182:183] op_sel_hi:[1,0]
	v_pk_mul_f32 v[34:35], v[34:35], v[182:183] op_sel_hi:[1,0]
	v_pk_mul_f32 v[32:33], v[32:33], v[184:185] op_sel_hi:[1,0]
	v_pk_mul_f32 v[30:31], v[30:31], v[184:185] op_sel_hi:[1,0]
	v_pk_mul_f32 v[44:45], v[44:45], v[186:187] op_sel_hi:[1,0]
	v_pk_mul_f32 v[42:43], v[42:43], v[186:187] op_sel_hi:[1,0]
	v_pk_mul_f32 v[40:41], v[40:41], v[188:189] op_sel_hi:[1,0]
	v_pk_mul_f32 v[38:39], v[38:39], v[188:189] op_sel_hi:[1,0]
	v_pk_mul_f32 v[52:53], v[52:53], v[190:191] op_sel_hi:[1,0]
	v_pk_mul_f32 v[50:51], v[50:51], v[190:191] op_sel_hi:[1,0]
	v_pk_mul_f32 v[48:49], v[48:49], v[192:193] op_sel_hi:[1,0]
	v_pk_mul_f32 v[46:47], v[46:47], v[192:193] op_sel_hi:[1,0]
	v_pk_mul_f32 v[60:61], v[60:61], v[194:195] op_sel_hi:[1,0]
	v_pk_mul_f32 v[58:59], v[58:59], v[194:195] op_sel_hi:[1,0]
	v_pk_mul_f32 v[56:57], v[56:57], v[196:197] op_sel_hi:[1,0]
	v_pk_mul_f32 v[54:55], v[54:55], v[196:197] op_sel_hi:[1,0]
	v_pk_mul_f32 v[68:69], v[68:69], v[198:199] op_sel_hi:[1,0]
	v_pk_mul_f32 v[66:67], v[66:67], v[198:199] op_sel_hi:[1,0]
	v_pk_mul_f32 v[64:65], v[64:65], v[200:201] op_sel_hi:[1,0]
	v_pk_mul_f32 v[62:63], v[62:63], v[200:201] op_sel_hi:[1,0]

.LBB0_337:
	s_or_b64 exec, exec, s[10:11]
	s_waitcnt lgkmcnt(0)
	s_cmp_lg_u64 s[8:9], 0
	s_cbranch_scc0 .LBB0_339
	v_lshl_add_u64 v[4:5], v[162:163], 2, s[8:9]
	global_load_dword v170, v[4:5], off
	global_load_dword v172, v[4:5], off offset:16
	global_load_dword v174, v[4:5], off offset:32
	global_load_dword v176, v[4:5], off offset:48
	global_load_dword v178, v[4:5], off offset:64
	global_load_dword v180, v[4:5], off offset:80
	global_load_dword v182, v[4:5], off offset:96
	global_load_dword v184, v[4:5], off offset:112
	global_load_dword v186, v[4:5], off offset:128
	global_load_dword v188, v[4:5], off offset:144
	global_load_dword v190, v[4:5], off offset:160
	global_load_dword v192, v[4:5], off offset:176
	global_load_dword v194, v[4:5], off offset:192
	global_load_dword v196, v[4:5], off offset:208
	global_load_dword v198, v[4:5], off offset:224
	global_load_dword v200, v[4:5], off offset:240
	s_waitcnt vmcnt(0)
	v_pk_mul_f32 v[72:73], v[72:73], v[170:171] op_sel_hi:[1,0]
	v_pk_mul_f32 v[70:71], v[70:71], v[170:171] op_sel_hi:[1,0]
	v_pk_mul_f32 v[76:77], v[76:77], v[172:173] op_sel_hi:[1,0]
	v_pk_mul_f32 v[74:75], v[74:75], v[172:173] op_sel_hi:[1,0]
	v_pk_mul_f32 v[80:81], v[80:81], v[174:175] op_sel_hi:[1,0]
	v_pk_mul_f32 v[78:79], v[78:79], v[174:175] op_sel_hi:[1,0]
	v_pk_mul_f32 v[84:85], v[84:85], v[176:177] op_sel_hi:[1,0]
	v_pk_mul_f32 v[82:83], v[82:83], v[176:177] op_sel_hi:[1,0]
	v_pk_mul_f32 v[88:89], v[88:89], v[178:179] op_sel_hi:[1,0]
	v_pk_mul_f32 v[86:87], v[86:87], v[178:179] op_sel_hi:[1,0]
	v_pk_mul_f32 v[92:93], v[92:93], v[180:181] op_sel_hi:[1,0]
	v_pk_mul_f32 v[90:91], v[90:91], v[180:181] op_sel_hi:[1,0]
	v_pk_mul_f32 v[96:97], v[96:97], v[182:183] op_sel_hi:[1,0]
	v_pk_mul_f32 v[94:95], v[94:95], v[182:183] op_sel_hi:[1,0]
	v_pk_mul_f32 v[100:101], v[100:101], v[184:185] op_sel_hi:[1,0]
	v_pk_mul_f32 v[98:99], v[98:99], v[184:185] op_sel_hi:[1,0]
	v_pk_mul_f32 v[104:105], v[104:105], v[186:187] op_sel_hi:[1,0]
	v_pk_mul_f32 v[102:103], v[102:103], v[186:187] op_sel_hi:[1,0]
	v_pk_mul_f32 v[108:109], v[108:109], v[188:189] op_sel_hi:[1,0]
	v_pk_mul_f32 v[106:107], v[106:107], v[188:189] op_sel_hi:[1,0]
	v_pk_mul_f32 v[112:113], v[112:113], v[190:191] op_sel_hi:[1,0]
	v_pk_mul_f32 v[110:111], v[110:111], v[190:191] op_sel_hi:[1,0]
	v_pk_mul_f32 v[116:117], v[116:117], v[192:193] op_sel_hi:[1,0]
	v_pk_mul_f32 v[114:115], v[114:115], v[192:193] op_sel_hi:[1,0]
	v_pk_mul_f32 v[120:121], v[120:121], v[194:195] op_sel_hi:[1,0]
	v_pk_mul_f32 v[118:119], v[118:119], v[194:195] op_sel_hi:[1,0]
	v_pk_mul_f32 v[124:125], v[124:125], v[196:197] op_sel_hi:[1,0]
	v_pk_mul_f32 v[122:123], v[122:123], v[196:197] op_sel_hi:[1,0]
	v_pk_mul_f32 v[128:129], v[128:129], v[198:199] op_sel_hi:[1,0]
	v_pk_mul_f32 v[126:127], v[126:127], v[198:199] op_sel_hi:[1,0]
	v_pk_mul_f32 v[132:133], v[132:133], v[200:201] op_sel_hi:[1,0]
	v_pk_mul_f32 v[130:131], v[130:131], v[200:201] op_sel_hi:[1,0]

.LBB0_372:
	s_or_b64 exec, exec, s[12:13]
	s_waitcnt lgkmcnt(0)
	s_cmp_lg_u64 s[10:11], 0
	s_cbranch_scc0 .LBB0_374
	v_lshl_add_u64 v[4:5], v[4:5], 2, s[10:11]
	global_load_dword v170, v[4:5], off
	global_load_dword v172, v[4:5], off offset:16
	global_load_dword v174, v[4:5], off offset:32
	global_load_dword v176, v[4:5], off offset:48
	global_load_dword v178, v[4:5], off offset:64
	global_load_dword v180, v[4:5], off offset:80
	global_load_dword v182, v[4:5], off offset:96
	global_load_dword v184, v[4:5], off offset:112
	global_load_dword v186, v[4:5], off offset:128
	global_load_dword v188, v[4:5], off offset:144
	global_load_dword v190, v[4:5], off offset:160
	global_load_dword v192, v[4:5], off offset:176
	global_load_dword v194, v[4:5], off offset:192
	global_load_dword v196, v[4:5], off offset:208
	global_load_dword v198, v[4:5], off offset:224
	global_load_dword v200, v[4:5], off offset:240
	s_waitcnt vmcnt(0)
	v_pk_mul_f32 v[8:9], v[8:9], v[170:171] op_sel_hi:[1,0]
	v_pk_mul_f32 v[6:7], v[6:7], v[170:171] op_sel_hi:[1,0]
	v_pk_mul_f32 v[12:13], v[12:13], v[172:173] op_sel_hi:[1,0]
	v_pk_mul_f32 v[10:11], v[10:11], v[172:173] op_sel_hi:[1,0]
	v_pk_mul_f32 v[20:21], v[20:21], v[174:175] op_sel_hi:[1,0]
	v_pk_mul_f32 v[18:19], v[18:19], v[174:175] op_sel_hi:[1,0]
	v_pk_mul_f32 v[16:17], v[16:17], v[176:177] op_sel_hi:[1,0]
	v_pk_mul_f32 v[14:15], v[14:15], v[176:177] op_sel_hi:[1,0]
	v_pk_mul_f32 v[28:29], v[28:29], v[178:179] op_sel_hi:[1,0]
	v_pk_mul_f32 v[26:27], v[26:27], v[178:179] op_sel_hi:[1,0]
	v_pk_mul_f32 v[24:25], v[24:25], v[180:181] op_sel_hi:[1,0]
	v_pk_mul_f32 v[22:23], v[22:23], v[180:181] op_sel_hi:[1,0]
	v_pk_mul_f32 v[36:37], v[36:37], v[182:183] op_sel_hi:[1,0]
	v_pk_mul_f32 v[34:35], v[34:35], v[182:183] op_sel_hi:[1,0]
	v_pk_mul_f32 v[32:33], v[32:33], v[184:185] op_sel_hi:[1,0]
	v_pk_mul_f32 v[30:31], v[30:31], v[184:185] op_sel_hi:[1,0]
	v_pk_mul_f32 v[44:45], v[44:45], v[186:187] op_sel_hi:[1,0]
	v_pk_mul_f32 v[42:43], v[42:43], v[186:187] op_sel_hi:[1,0]
	v_pk_mul_f32 v[40:41], v[40:41], v[188:189] op_sel_hi:[1,0]
	v_pk_mul_f32 v[38:39], v[38:39], v[188:189] op_sel_hi:[1,0]
	v_pk_mul_f32 v[52:53], v[52:53], v[190:191] op_sel_hi:[1,0]
	v_pk_mul_f32 v[50:51], v[50:51], v[190:191] op_sel_hi:[1,0]
	v_pk_mul_f32 v[48:49], v[48:49], v[192:193] op_sel_hi:[1,0]
	v_pk_mul_f32 v[46:47], v[46:47], v[192:193] op_sel_hi:[1,0]
	v_pk_mul_f32 v[60:61], v[60:61], v[194:195] op_sel_hi:[1,0]
	v_pk_mul_f32 v[58:59], v[58:59], v[194:195] op_sel_hi:[1,0]
	v_pk_mul_f32 v[56:57], v[56:57], v[196:197] op_sel_hi:[1,0]
	v_pk_mul_f32 v[54:55], v[54:55], v[196:197] op_sel_hi:[1,0]
	v_pk_mul_f32 v[68:69], v[68:69], v[198:199] op_sel_hi:[1,0]
	v_pk_mul_f32 v[66:67], v[66:67], v[198:199] op_sel_hi:[1,0]
	v_pk_mul_f32 v[64:65], v[64:65], v[200:201] op_sel_hi:[1,0]
	v_pk_mul_f32 v[62:63], v[62:63], v[200:201] op_sel_hi:[1,0]
